# MLA attention tile body: all twelve K fragment LDS reads of the QK part issued up front (seven into fresh registers) behind counted waits
# speedup vs baseline: 1.0100x; 1.0020x over previous
; #define MFMA(a, b, c) __builtin_amdgcn_mfma_f32_16x16x32_bf16((a), (b), (c), 0, 0, 0)
; template <int DK, bool BIAS> ...
;     ...
; #pragma unroll
;       for (int ks = 0; ks < KS; ++ks)
; #pragma unroll
;         for (int kt = 0; kt < 4; ++kt) { const bf16x8 ak = *(const bf16x8*)(Ksm + (buf * 64 + 16 * kt + fr) * KST + 32 * ks + 8 * fq);
; #pragma unroll
;           for (int qi = 0; qi < 2; ++qi) S[kt][qi] = MFMA(ak, qf[qi][ks], S[kt][qi]); }
;       bf16x8 pf[2][2];
;       if (64 * j + 63 > q0 + 32 * w) {
; #pragma unroll
;         for (int qi = 0; qi < 2; ++qi) { const int qg = q0 + 32 * w + 16 * qi + fr;
; #pragma unroll
;           for (int kt = 0; kt < 4; ++kt)
; #pragma unroll
;             for (int r = 0; r < 4; ++r) { const int kg = 64 * j + 16 * kt + 4 * fq + r; if (kg > qg) S[kt][qi][r] = -1e30f; } }
;       }
.LBB0_1862:
	s_and_saveexec_b64 s[0:1], s[8:9]
	s_cbranch_execz .LBB0_1868
	v_cmp_le_i32_e32 vcc, s58, v201
	s_and_saveexec_b64 s[94:95], vcc
	s_cbranch_execz .LBB0_1867
	ds_read_b128 v[80:83], v202
	ds_read_b128 v[156:159], v202 offset:64
	ds_read_b128 v[88:91], v202 offset:3328
	ds_read_b128 v[96:99], v202 offset:6656
	ds_read_b128 v[104:107], v202 offset:9984
	ds_read_b128 v[210:213], v202 offset:3392
	ds_read_b128 v[214:217], v202 offset:6720
	ds_read_b128 v[218:221], v202 offset:10048
	ds_read_b128 v[222:225], v202 offset:128
	ds_read_b128 v[226:229], v202 offset:3456
	ds_read_b128 v[230:233], v202 offset:10112
	ds_read_b128 v[234:237], v202 offset:6784
	s_add_i32 s18, s58, 63
	v_cmp_gt_i32_e32 vcc, s18, v153
	s_waitcnt lgkmcnt(11)
	v_mfma_f32_16x16x32_bf16 v[84:87], v[80:83], v[4:7], 0
	v_mfma_f32_16x16x32_bf16 v[80:83], v[80:83], v[8:11], 0
	s_waitcnt lgkmcnt(10)
	v_mfma_f32_16x16x32_bf16 v[84:87], v[156:159], v[0:3], v[84:87]
	v_mfma_f32_16x16x32_bf16 v[80:83], v[156:159], v[20:23], v[80:83]
	s_waitcnt lgkmcnt(9)
	v_mfma_f32_16x16x32_bf16 v[92:95], v[88:91], v[4:7], 0
	v_mfma_f32_16x16x32_bf16 v[88:91], v[88:91], v[8:11], 0
	s_waitcnt lgkmcnt(6)
	v_mfma_f32_16x16x32_bf16 v[92:95], v[210:213], v[0:3], v[92:95]
	v_mfma_f32_16x16x32_bf16 v[156:159], v[210:213], v[20:23], v[88:91]
	v_mfma_f32_16x16x32_bf16 v[100:103], v[96:99], v[4:7], 0
	v_mfma_f32_16x16x32_bf16 v[96:99], v[96:99], v[8:11], 0
	s_waitcnt lgkmcnt(5)
	v_mfma_f32_16x16x32_bf16 v[160:163], v[214:217], v[0:3], v[100:103]
	v_mfma_f32_16x16x32_bf16 v[164:167], v[214:217], v[20:23], v[96:99]
	v_mfma_f32_16x16x32_bf16 v[108:111], v[104:107], v[4:7], 0
	v_mfma_f32_16x16x32_bf16 v[104:107], v[104:107], v[8:11], 0
	s_waitcnt lgkmcnt(4)
	v_mfma_f32_16x16x32_bf16 v[108:111], v[218:221], v[0:3], v[108:111]
	v_mfma_f32_16x16x32_bf16 v[168:171], v[218:221], v[20:23], v[104:107]
	s_waitcnt lgkmcnt(3)
	v_mfma_f32_16x16x32_bf16 v[100:103], v[222:225], v[12:15], v[84:87]
	v_mfma_f32_16x16x32_bf16 v[88:91], v[222:225], v[16:19], v[80:83]
	s_waitcnt lgkmcnt(2)
	v_mfma_f32_16x16x32_bf16 v[96:99], v[226:229], v[12:15], v[92:95]
	v_mfma_f32_16x16x32_bf16 v[84:87], v[226:229], v[16:19], v[156:159]
	s_waitcnt lgkmcnt(0)
	v_mfma_f32_16x16x32_bf16 v[104:107], v[234:237], v[12:15], v[160:163]
	v_mfma_f32_16x16x32_bf16 v[80:83], v[234:237], v[16:19], v[164:167]
	v_mfma_f32_16x16x32_bf16 v[108:111], v[230:233], v[12:15], v[108:111]
	v_mfma_f32_16x16x32_bf16 v[92:95], v[230:233], v[16:19], v[168:171]
	s_and_saveexec_b64 s[18:19], vcc
	s_cbranch_execz .LBB0_1866
	v_add_u32_e32 v131, s58, v200
	v_mov_b32_e32 v156, s30
	v_cmp_gt_i32_e32 vcc, v131, v194
	v_add_u32_e32 v157, 3, v131
	v_add_u32_e32 v158, 16, v131
	v_cndmask_b32_e32 v155, v100, v156, vcc
	v_cmp_lt_i32_e32 vcc, v131, v194
	v_add_u32_e32 v159, 17, v131
	v_add_u32_e32 v160, 18, v131
	v_cndmask_b32_e32 v100, v155, v100, vcc
	v_add_u32_e32 v155, 2, v131
	v_cndmask_b32_e32 v101, v193, v101, vcc
	v_cmp_le_i32_e32 vcc, v155, v194
	v_add_u32_e32 v161, 19, v131
	v_add_u32_e32 v162, 32, v131
	v_cndmask_b32_e32 v102, v193, v102, vcc
	v_cmp_le_i32_e32 vcc, v157, v194
	v_add_u32_e32 v163, 33, v131
	v_add_u32_e32 v164, 34, v131
	v_cndmask_b32_e32 v103, v193, v103, vcc
	v_cmp_gt_i32_e32 vcc, v158, v194
	v_add_u32_e32 v165, 35, v131
	v_add_u32_e32 v166, 48, v131
	v_cndmask_b32_e32 v96, v96, v156, vcc
	v_cmp_le_i32_e32 vcc, v159, v194
	v_add_u32_e32 v167, 49, v131
	v_add_u32_e32 v168, 50, v131
	v_cndmask_b32_e32 v97, v193, v97, vcc
	v_cmp_le_i32_e32 vcc, v160, v194
	v_add_u32_e32 v169, 51, v131
	s_nop 0
	v_cndmask_b32_e32 v98, v193, v98, vcc
	v_cmp_le_i32_e32 vcc, v161, v194
	v_cmp_gt_i32_e64 s[100:101], v162, v194
	s_nop 0
	v_cndmask_b32_e32 v99, v193, v99, vcc
	v_cndmask_b32_e64 v104, v104, v156, s[100:101]
	v_cmp_le_i32_e32 vcc, v163, v194
	v_cmp_le_i32_e64 s[100:101], v164, v194
	s_nop 0
	v_cndmask_b32_e32 v105, v193, v105, vcc
	v_cndmask_b32_e64 v106, v193, v106, s[100:101]
	v_cmp_le_i32_e32 vcc, v165, v194
	v_cmp_gt_i32_e64 s[100:101], v166, v194
	s_nop 0
	v_cndmask_b32_e32 v107, v193, v107, vcc
	v_cndmask_b32_e64 v108, v108, v156, s[100:101]
	v_cmp_le_i32_e32 vcc, v167, v194
	v_cmp_le_i32_e64 s[100:101], v168, v194
	s_nop 0
	v_cndmask_b32_e32 v109, v193, v109, vcc
	v_cndmask_b32_e64 v110, v193, v110, s[100:101]
	v_cmp_le_i32_e32 vcc, v169, v194
	v_cmp_gt_i32_e64 s[100:101], v131, v195
	s_nop 0
	v_cndmask_b32_e32 v111, v193, v111, vcc
	v_cndmask_b32_e64 v156, v88, v156, s[100:101]
	v_cmp_lt_i32_e32 vcc, v131, v195
	s_nop 1
	v_cndmask_b32_e32 v88, v156, v88, vcc
	v_cndmask_b32_e32 v89, v193, v89, vcc
	v_cmp_le_i32_e32 vcc, v155, v195
	v_mov_b32_e32 v156, s30
	s_nop 0
	v_cndmask_b32_e32 v90, v193, v90, vcc
	v_cmp_le_i32_e32 vcc, v157, v195
	v_cmp_gt_i32_e64 s[100:101], v158, v195
	s_nop 0
	v_cndmask_b32_e32 v91, v193, v91, vcc
	v_cndmask_b32_e64 v84, v84, v156, s[100:101]
	v_cmp_le_i32_e32 vcc, v159, v195
	v_cmp_le_i32_e64 s[100:101], v160, v195
	s_nop 0
	v_cndmask_b32_e32 v85, v193, v85, vcc
	v_cndmask_b32_e64 v86, v193, v86, s[100:101]
	v_cmp_le_i32_e32 vcc, v161, v195
	v_cmp_gt_i32_e64 s[100:101], v162, v195
	s_nop 0
	v_cndmask_b32_e32 v87, v193, v87, vcc
	v_cndmask_b32_e64 v80, v80, v156, s[100:101]
	v_cmp_le_i32_e32 vcc, v163, v195
	v_cmp_le_i32_e64 s[100:101], v164, v195
	s_nop 0
	v_cndmask_b32_e32 v81, v193, v81, vcc
	v_cndmask_b32_e64 v82, v193, v82, s[100:101]
	v_cmp_le_i32_e32 vcc, v165, v195
	v_cmp_gt_i32_e64 s[100:101], v166, v195
	s_nop 0
	v_cndmask_b32_e32 v83, v193, v83, vcc
	v_cndmask_b32_e64 v92, v92, v156, s[100:101]
	v_cmp_le_i32_e32 vcc, v167, v195
	v_cmp_le_i32_e64 s[100:101], v168, v195
	s_nop 0
	v_cndmask_b32_e32 v93, v193, v93, vcc
	v_cndmask_b32_e64 v94, v193, v94, s[100:101]
	v_cmp_le_i32_e32 vcc, v169, v195
	s_nop 1
	v_cndmask_b32_e32 v95, v193, v95, vcc

; #define MFMA(a, b, c) __builtin_amdgcn_mfma_f32_16x16x32_bf16((a), (b), (c), 0, 0, 0)
; template <int DK, bool BIAS> ...
;     ...
; #pragma unroll
;       for (int ks = 0; ks < KS; ++ks)
; #pragma unroll
;         for (int kt = 0; kt < 4; ++kt) { const bf16x8 ak = *(const bf16x8*)(Ksm + (buf * 64 + 16 * kt + fr) * KST + 32 * ks + 8 * fq);
; #pragma unroll
;           for (int qi = 0; qi < 2; ++qi) S[kt][qi] = MFMA(ak, qf[qi][ks], S[kt][qi]); }
;       bf16x8 pf[2][2];
;       if (64 * j + 63 > q0 + 32 * w) {
; #pragma unroll
;         for (int qi = 0; qi < 2; ++qi) { const int qg = q0 + 32 * w + 16 * qi + fr;
; #pragma unroll
;           for (int kt = 0; kt < 4; ++kt)
; #pragma unroll
;             for (int r = 0; r < 4; ++r) { const int kg = 64 * j + 16 * kt + 4 * fq + r; if (kg > qg) S[kt][qi][r] = -1e30f; } }
;       }
.LBB0_1885:
	s_add_i32 s16, s58, 64
	v_cmp_le_i32_e32 vcc, s16, v201
	s_and_saveexec_b64 s[16:17], vcc
	s_cbranch_execz .LBB0_1889
	ds_read_b128 v[80:83], v205
	ds_read_b128 v[156:159], v205 offset:64
	ds_read_b128 v[88:91], v205 offset:3328
	ds_read_b128 v[96:99], v205 offset:6656
	ds_read_b128 v[104:107], v205 offset:9984
	ds_read_b128 v[210:213], v205 offset:3392
	ds_read_b128 v[214:217], v205 offset:6720
	ds_read_b128 v[218:221], v205 offset:10048
	ds_read_b128 v[222:225], v205 offset:128
	ds_read_b128 v[226:229], v205 offset:6784
	ds_read_b128 v[230:233], v205 offset:3456
	ds_read_b128 v[234:237], v205 offset:10112
	s_add_i32 s18, s58, 0x7f
	v_cmp_gt_i32_e32 vcc, s18, v153
	s_waitcnt lgkmcnt(11)
	v_mfma_f32_16x16x32_bf16 v[84:87], v[80:83], v[4:7], 0
	v_mfma_f32_16x16x32_bf16 v[80:83], v[80:83], v[8:11], 0
	s_waitcnt lgkmcnt(10)
	v_mfma_f32_16x16x32_bf16 v[84:87], v[156:159], v[0:3], v[84:87]
	v_mfma_f32_16x16x32_bf16 v[80:83], v[156:159], v[20:23], v[80:83]
	s_waitcnt lgkmcnt(9)
	v_mfma_f32_16x16x32_bf16 v[92:95], v[88:91], v[4:7], 0
	v_mfma_f32_16x16x32_bf16 v[88:91], v[88:91], v[8:11], 0
	s_waitcnt lgkmcnt(6)
	v_mfma_f32_16x16x32_bf16 v[92:95], v[210:213], v[0:3], v[92:95]
	v_mfma_f32_16x16x32_bf16 v[156:159], v[210:213], v[20:23], v[88:91]
	v_mfma_f32_16x16x32_bf16 v[100:103], v[96:99], v[4:7], 0
	v_mfma_f32_16x16x32_bf16 v[96:99], v[96:99], v[8:11], 0
	s_waitcnt lgkmcnt(5)
	v_mfma_f32_16x16x32_bf16 v[160:163], v[214:217], v[0:3], v[100:103]
	v_mfma_f32_16x16x32_bf16 v[164:167], v[214:217], v[20:23], v[96:99]
	v_mfma_f32_16x16x32_bf16 v[108:111], v[104:107], v[4:7], 0
	v_mfma_f32_16x16x32_bf16 v[104:107], v[104:107], v[8:11], 0
	s_waitcnt lgkmcnt(4)
	v_mfma_f32_16x16x32_bf16 v[108:111], v[218:221], v[0:3], v[108:111]
	v_mfma_f32_16x16x32_bf16 v[168:171], v[218:221], v[20:23], v[104:107]
	s_waitcnt lgkmcnt(3)
	v_mfma_f32_16x16x32_bf16 v[100:103], v[222:225], v[12:15], v[84:87]
	v_mfma_f32_16x16x32_bf16 v[88:91], v[222:225], v[16:19], v[80:83]
	s_waitcnt lgkmcnt(1)
	v_mfma_f32_16x16x32_bf16 v[96:99], v[230:233], v[12:15], v[92:95]
	v_mfma_f32_16x16x32_bf16 v[80:83], v[230:233], v[16:19], v[156:159]
	v_mfma_f32_16x16x32_bf16 v[104:107], v[226:229], v[12:15], v[160:163]
	v_mfma_f32_16x16x32_bf16 v[84:87], v[226:229], v[16:19], v[164:167]
	s_waitcnt lgkmcnt(0)
	v_mfma_f32_16x16x32_bf16 v[108:111], v[234:237], v[12:15], v[108:111]
	v_mfma_f32_16x16x32_bf16 v[92:95], v[234:237], v[16:19], v[168:171]
	s_and_saveexec_b64 s[18:19], vcc
	s_cbranch_execz .LBB0_1888
	v_add_u32_e32 v131, s58, v200
	v_add_u32_e32 v155, 64, v131
	v_mov_b32_e32 v156, s30
	v_cmp_gt_i32_e32 vcc, v155, v194
	v_add_u32_e32 v157, 0x42, v131
	v_add_u32_e32 v158, 0x43, v131
	v_cndmask_b32_e32 v156, v100, v156, vcc
	v_cmp_lt_i32_e32 vcc, v155, v194
	v_add_u32_e32 v159, 0x50, v131
	v_add_u32_e32 v160, 0x51, v131
	v_cndmask_b32_e32 v100, v156, v100, vcc
	v_cndmask_b32_e32 v101, v193, v101, vcc
	v_cmp_le_i32_e32 vcc, v157, v194
	v_mov_b32_e32 v156, s30
	v_add_u32_e32 v161, 0x52, v131
	v_cndmask_b32_e32 v102, v193, v102, vcc
	v_cmp_le_i32_e32 vcc, v158, v194
	v_add_u32_e32 v162, 0x53, v131
	v_add_u32_e32 v163, 0x60, v131
	v_cndmask_b32_e32 v103, v193, v103, vcc
	v_cmp_gt_i32_e32 vcc, v159, v194
	v_add_u32_e32 v164, 0x61, v131
	v_add_u32_e32 v165, 0x62, v131
	v_cndmask_b32_e32 v96, v96, v156, vcc
	v_cmp_le_i32_e32 vcc, v160, v194
	v_add_u32_e32 v166, 0x63, v131
	v_add_u32_e32 v167, 0x70, v131
	v_cndmask_b32_e32 v97, v193, v97, vcc
	v_cmp_le_i32_e32 vcc, v161, v194
	v_add_u32_e32 v168, 0x71, v131
	v_add_u32_e32 v169, 0x72, v131
	v_cndmask_b32_e32 v98, v193, v98, vcc
	v_cmp_le_i32_e32 vcc, v162, v194
	v_add_u32_e32 v131, 0x73, v131
	s_nop 0
	v_cndmask_b32_e32 v99, v193, v99, vcc
	v_cmp_gt_i32_e32 vcc, v163, v194
	v_cmp_le_i32_e64 s[100:101], v164, v194
	s_nop 0
	v_cndmask_b32_e32 v104, v104, v156, vcc
	v_cndmask_b32_e64 v105, v193, v105, s[100:101]
	v_cmp_le_i32_e32 vcc, v165, v194
	v_cmp_le_i32_e64 s[100:101], v166, v194
	s_nop 0
	v_cndmask_b32_e32 v106, v193, v106, vcc
	v_cndmask_b32_e64 v107, v193, v107, s[100:101]
	v_cmp_gt_i32_e32 vcc, v167, v194
	v_cmp_le_i32_e64 s[100:101], v168, v194
	s_nop 0
	v_cndmask_b32_e32 v108, v108, v156, vcc
	v_cndmask_b32_e64 v109, v193, v109, s[100:101]
	v_cmp_le_i32_e32 vcc, v169, v194
	v_cmp_le_i32_e64 s[100:101], v131, v194
	s_nop 0
	v_cndmask_b32_e32 v110, v193, v110, vcc
	v_cndmask_b32_e64 v111, v193, v111, s[100:101]
	v_cmp_gt_i32_e32 vcc, v155, v195
	s_nop 1
	v_cndmask_b32_e32 v156, v88, v156, vcc
	v_cmp_lt_i32_e32 vcc, v155, v195
	s_nop 1
	v_cndmask_b32_e32 v88, v156, v88, vcc
	v_cndmask_b32_e32 v89, v193, v89, vcc
	v_cmp_le_i32_e32 vcc, v157, v195
	v_mov_b32_e32 v156, s30
	s_nop 0
	v_cndmask_b32_e32 v90, v193, v90, vcc
	v_cmp_le_i32_e32 vcc, v158, v195
	v_cmp_gt_i32_e64 s[100:101], v159, v195
	s_nop 0
	v_cndmask_b32_e32 v91, v193, v91, vcc
	v_cndmask_b32_e64 v80, v80, v156, s[100:101]
	v_cmp_le_i32_e32 vcc, v160, v195
	v_cmp_le_i32_e64 s[100:101], v161, v195
	s_nop 0
	v_cndmask_b32_e32 v81, v193, v81, vcc
	v_cndmask_b32_e64 v82, v193, v82, s[100:101]
	v_cmp_le_i32_e32 vcc, v162, v195
	v_cmp_gt_i32_e64 s[100:101], v163, v195
	s_nop 0
	v_cndmask_b32_e32 v83, v193, v83, vcc
	v_cndmask_b32_e64 v84, v84, v156, s[100:101]
	v_cmp_le_i32_e32 vcc, v164, v195
	v_cmp_le_i32_e64 s[100:101], v165, v195
	s_nop 0
	v_cndmask_b32_e32 v85, v193, v85, vcc
	v_cndmask_b32_e64 v86, v193, v86, s[100:101]
	v_cmp_le_i32_e32 vcc, v166, v195
	v_cmp_gt_i32_e64 s[100:101], v167, v195
	s_nop 0
	v_cndmask_b32_e32 v87, v193, v87, vcc
	v_cndmask_b32_e64 v92, v92, v156, s[100:101]
	v_cmp_le_i32_e32 vcc, v168, v195
	v_cmp_le_i32_e64 s[100:101], v169, v195
	s_nop 0
	v_cndmask_b32_e32 v93, v193, v93, vcc
	v_cndmask_b32_e64 v94, v193, v94, s[100:101]
	v_cmp_le_i32_e32 vcc, v131, v195
	s_nop 1
	v_cndmask_b32_e32 v95, v193, v95, vcc
